# grid barrier leader path: local release (XGEN atomic) issued before the leader's own acquire (vmcnt wait + buffer_inv) at 10 sites
# speedup vs baseline: 1.0061x; 1.0031x over previous
.LBB0_182:
	s_or_b64 exec, exec, s[2:3]
	s_mov_b64 s[2:3], exec
	v_mbcnt_lo_u32_b32 v0, s2, 0
	v_mbcnt_hi_u32_b32 v0, s3, v0
	v_cmp_eq_u32_e32 vcc, 0, v0
	s_and_saveexec_b64 s[8:9], vcc
	s_cbranch_execz .LBB0_184
	s_bcnt1_i32_b64 s2, s[2:3]
	v_mov_b32_e32 v0, s2
	global_atomic_add v235, v0, s[4:5] offset:1024
.LBB0_184:
	s_or_b64 exec, exec, s[8:9]
	s_waitcnt vmcnt(0)
	buffer_inv sc1
	s_waitcnt vmcnt(0)
.LBB0_185:
	s_or_b64 exec, exec, s[6:7]

.LBB0_300:
	s_or_b64 exec, exec, s[2:3]
	s_mov_b64 s[2:3], exec
	v_mbcnt_lo_u32_b32 v0, s2, 0
	v_mbcnt_hi_u32_b32 v0, s3, v0
	v_cmp_eq_u32_e32 vcc, 0, v0
	s_and_saveexec_b64 s[6:7], vcc
	s_cbranch_execz .LBB0_302
	s_bcnt1_i32_b64 s2, s[2:3]
	v_mov_b32_e32 v0, s2
	global_atomic_add v235, v0, s[4:5] offset:1024
.LBB0_302:
	s_or_b64 exec, exec, s[6:7]
	s_waitcnt vmcnt(0)
	buffer_inv sc1
	s_waitcnt vmcnt(0)

.LBB0_802:
	s_or_b64 exec, exec, s[8:9]
	s_waitcnt vmcnt(0)
	buffer_inv sc1
	s_waitcnt vmcnt(0)
.LBB0_803:
	s_or_b64 exec, exec, s[6:7]
